# out-GEMM in-place residual epilogue rewritten the same way (loads in flight, 32-bit offsets, parsed accumulator map)
# baseline (speedup 1.0000x reference)
; __device__ __forceinline__ unsigned cvt_pk_bf16(float lo, float hi) { unsigned r; asm("v_cvt_pk_bf16_f32 %0, %1, %2" : "=v"(r) : "v"(lo), "v"(hi)); return r; }
;     __device__ __forceinline__ void operator()(const Acc& acc, const Unit& u, int wr, int wc, int fr, int fq) const {
;         const bool isx = u.pm < 128; const int mb = isx ? (u.pm >> 4) : 8;
;         const size_t tile0 = (size_t)(isx ? u.pm : u.pm - 128) * 256 * D;
;         const float* sp32 = (const float*)(isx ? srcx : srcc) + tile0; const bf16_t* sp16 = (const bf16_t*)(isx ? srcx : srcc) + tile0;
;         float* dp32 = (float*)(isx ? dstx : dstc) + tile0; bf16_t* dp16 = (bf16_t*)(isx ? dstx : dstc) + tile0;
;         const int r0 = wr * 64 + fr, col0 = u.pn * 256 + wc * 32 + 8 * fq; const float* gp = gate + (size_t)mb * 9216 + col0;
;         f32x4 gv[2][2];
; #pragma unroll
;         for (int bj = 0; bj < 2; ++bj)
; #pragma unroll
;             for (int n = 0; n < 2; ++n) gv[bj][n] = *(const f32x4*)(gp + bj * 128 + n * 4) * f;
; #pragma unroll
;         for (int ai = 0; ai < 2; ++ai)
; #pragma unroll
;             for (int m = 0; m < 4; ++m) { const size_t off = (size_t)(r0 + ai * 128 + m * 16) * D + col0;
; #pragma unroll
;                 for (int bj = 0; bj < 2; ++bj) { const size_t o2 = off + bj * 128; f32x4 s0, s1;
;                     if (SRC32) { s0 = *(const f32x4*)(sp32 + o2); s1 = *(const f32x4*)(sp32 + o2 + 4); }
;                     else { const u32x4 q = *(const u32x4*)(sp16 + o2); s0 = (f32x4){bf2f(q.x & 0xffffu), bf2f(q.x >> 16), bf2f(q.y & 0xffffu), bf2f(q.y >> 16)}; s1 = (f32x4){bf2f(q.z & 0xffffu), bf2f(q.z >> 16), bf2f(q.w & 0xffffu), bf2f(q.w >> 16)}; }
;                     const f32x4 v0 = s0 + gv[bj][0] * acc[ai][bj][m][0], v1 = s1 + gv[bj][1] * acc[ai][bj][m][1];
;                     if (DST32) { *(f32x4*)(dp32 + o2) = v0; *(f32x4*)(dp32 + o2 + 4) = v1; }
;                     else { u32x4 w; w.x = cvt_pk_bf16(v0.x, v0.y); w.y = cvt_pk_bf16(v0.z, v0.w); w.z = cvt_pk_bf16(v1.x, v1.y); w.w = cvt_pk_bf16(v1.z, v1.w); *(u32x4*)(dp16 + o2) = w; } } }
.LBB0_923:
	s_add_i32 s23, s40, 0xffffff80
	s_and_b64 s[44:45], s[44:45], exec
	s_cselect_b32 s40, s40, s23
	s_ashr_i32 s41, s40, 31
	v_lshl_or_b32 v238, s34, 8, v199
	s_lshl_b64 s[34:35], s[42:43], 2
	s_add_u32 s42, s52, s34
	s_addc_u32 s43, s53, s35
	v_lshlrev_b32_e32 v196, 2, v238
	global_load_dwordx4 v[128:131], v196, s[42:43]
	global_load_dwordx4 v[132:135], v196, s[42:43] offset:16
	global_load_dwordx4 v[136:139], v196, s[42:43] offset:512
	global_load_dwordx4 v[140:143], v196, s[42:43] offset:528
	s_lshl_b64 s[34:35], s[40:41], 19
	s_add_u32 s40, s86, s34
	s_addc_u32 s41, s87, s35
	v_lshl_add_u32 v197, v238, 1, v164
	global_load_dwordx4 v[144:147], v197, s[40:41]
	global_load_dwordx4 v[148:151], v197, s[40:41] offset:256
	v_lshl_add_u32 v196, v238, 1, v174
	global_load_dwordx4 v[152:155], v196, s[40:41]
	global_load_dwordx4 v[156:159], v196, s[40:41] offset:256
	v_lshl_add_u32 v197, v238, 1, v176
	global_load_dwordx4 v[188:191], v197, s[40:41]
	global_load_dwordx4 v[208:211], v197, s[40:41] offset:256
	v_lshl_add_u32 v196, v238, 1, v178
	global_load_dwordx4 v[212:215], v196, s[40:41]
	global_load_dwordx4 v[216:219], v196, s[40:41] offset:256
	v_lshl_add_u32 v197, v238, 1, v166
	global_load_dwordx4 v[220:223], v197, s[40:41]
	global_load_dwordx4 v[224:227], v197, s[40:41] offset:256
	v_lshl_add_u32 v196, v238, 1, v168
	global_load_dwordx4 v[228:231], v196, s[40:41]
	global_load_dwordx4 v[232:235], v196, s[40:41] offset:256
	s_waitcnt vmcnt(11)
	v_lshlrev_b32_e32 v192, 16, v144
	v_and_b32_e32 v193, 0xffff0000, v144
	v_lshlrev_b32_e32 v194, 16, v145
	v_and_b32_e32 v195, 0xffff0000, v145
	v_lshlrev_b32_e32 v144, 16, v146
	v_and_b32_e32 v145, 0xffff0000, v146
	v_lshlrev_b32_e32 v146, 16, v147
	v_and_b32_e32 v147, 0xffff0000, v147
	v_pk_fma_f32 v[124:125], v[124:125], v[128:129], v[192:193]
	v_pk_fma_f32 v[126:127], v[126:127], v[130:131], v[194:195]
	v_pk_fma_f32 v[120:121], v[120:121], v[132:133], v[144:145]
	v_pk_fma_f32 v[122:123], v[122:123], v[134:135], v[146:147]
	v_cvt_pk_bf16_f32 v124, v124, v125
	v_cvt_pk_bf16_f32 v125, v126, v127
	v_cvt_pk_bf16_f32 v126, v120, v121
	v_cvt_pk_bf16_f32 v127, v122, v123
	s_waitcnt vmcnt(10)
	v_lshlrev_b32_e32 v192, 16, v148
	v_and_b32_e32 v193, 0xffff0000, v148
	v_lshlrev_b32_e32 v194, 16, v149
	v_and_b32_e32 v195, 0xffff0000, v149
	v_lshlrev_b32_e32 v148, 16, v150
	v_and_b32_e32 v149, 0xffff0000, v150
	v_lshlrev_b32_e32 v150, 16, v151
	v_and_b32_e32 v151, 0xffff0000, v151
	v_pk_fma_f32 v[108:109], v[108:109], v[136:137], v[192:193]
	v_pk_fma_f32 v[110:111], v[110:111], v[138:139], v[194:195]
	v_pk_fma_f32 v[104:105], v[104:105], v[140:141], v[148:149]
	v_pk_fma_f32 v[106:107], v[106:107], v[142:143], v[150:151]
	v_cvt_pk_bf16_f32 v108, v108, v109
	v_cvt_pk_bf16_f32 v109, v110, v111
	v_cvt_pk_bf16_f32 v110, v104, v105
	v_cvt_pk_bf16_f32 v111, v106, v107
	s_waitcnt vmcnt(9)
	v_lshlrev_b32_e32 v192, 16, v152
	v_and_b32_e32 v193, 0xffff0000, v152
	v_lshlrev_b32_e32 v194, 16, v153
	v_and_b32_e32 v195, 0xffff0000, v153
	v_lshlrev_b32_e32 v152, 16, v154
	v_and_b32_e32 v153, 0xffff0000, v154
	v_lshlrev_b32_e32 v154, 16, v155
	v_and_b32_e32 v155, 0xffff0000, v155
	v_pk_fma_f32 v[116:117], v[116:117], v[128:129], v[192:193]
	v_pk_fma_f32 v[118:119], v[118:119], v[130:131], v[194:195]
	v_pk_fma_f32 v[112:113], v[112:113], v[132:133], v[152:153]
	v_pk_fma_f32 v[114:115], v[114:115], v[134:135], v[154:155]
	v_cvt_pk_bf16_f32 v116, v116, v117
	v_cvt_pk_bf16_f32 v117, v118, v119
	v_cvt_pk_bf16_f32 v118, v112, v113
	v_cvt_pk_bf16_f32 v119, v114, v115
	s_waitcnt vmcnt(8)
	v_lshlrev_b32_e32 v192, 16, v156
	v_and_b32_e32 v193, 0xffff0000, v156
	v_lshlrev_b32_e32 v194, 16, v157
	v_and_b32_e32 v195, 0xffff0000, v157
	v_lshlrev_b32_e32 v156, 16, v158
	v_and_b32_e32 v157, 0xffff0000, v158
	v_lshlrev_b32_e32 v158, 16, v159
	v_and_b32_e32 v159, 0xffff0000, v159
	v_pk_fma_f32 v[100:101], v[100:101], v[136:137], v[192:193]
	v_pk_fma_f32 v[102:103], v[102:103], v[138:139], v[194:195]
	v_pk_fma_f32 v[96:97], v[96:97], v[140:141], v[156:157]
	v_pk_fma_f32 v[98:99], v[98:99], v[142:143], v[158:159]
	v_cvt_pk_bf16_f32 v100, v100, v101
	v_cvt_pk_bf16_f32 v101, v102, v103
	v_cvt_pk_bf16_f32 v102, v96, v97
	v_cvt_pk_bf16_f32 v103, v98, v99
	v_lshl_add_u32 v197, v238, 1, v170
	global_load_dwordx4 v[144:147], v197, s[40:41]
	global_load_dwordx4 v[148:151], v197, s[40:41] offset:256
	v_lshl_add_u32 v196, v238, 1, v172
	global_load_dwordx4 v[152:155], v196, s[40:41]
	global_load_dwordx4 v[156:159], v196, s[40:41] offset:256
	s_waitcnt vmcnt(11)
	v_lshlrev_b32_e32 v192, 16, v188
	v_and_b32_e32 v193, 0xffff0000, v188
	v_lshlrev_b32_e32 v194, 16, v189
	v_and_b32_e32 v195, 0xffff0000, v189
	v_lshlrev_b32_e32 v188, 16, v190
	v_and_b32_e32 v189, 0xffff0000, v190
	v_lshlrev_b32_e32 v190, 16, v191
	v_and_b32_e32 v191, 0xffff0000, v191
	v_pk_fma_f32 v[92:93], v[92:93], v[128:129], v[192:193]
	v_pk_fma_f32 v[94:95], v[94:95], v[130:131], v[194:195]
	v_pk_fma_f32 v[88:89], v[88:89], v[132:133], v[188:189]
	v_pk_fma_f32 v[90:91], v[90:91], v[134:135], v[190:191]
	v_cvt_pk_bf16_f32 v92, v92, v93
	v_cvt_pk_bf16_f32 v93, v94, v95
	v_cvt_pk_bf16_f32 v94, v88, v89
	v_cvt_pk_bf16_f32 v95, v90, v91
	s_waitcnt vmcnt(10)
	v_lshlrev_b32_e32 v192, 16, v208
	v_and_b32_e32 v193, 0xffff0000, v208
	v_lshlrev_b32_e32 v194, 16, v209
	v_and_b32_e32 v195, 0xffff0000, v209
	v_lshlrev_b32_e32 v208, 16, v210
	v_and_b32_e32 v209, 0xffff0000, v210
	v_lshlrev_b32_e32 v210, 16, v211
	v_and_b32_e32 v211, 0xffff0000, v211
	v_pk_fma_f32 v[84:85], v[84:85], v[136:137], v[192:193]
	v_pk_fma_f32 v[86:87], v[86:87], v[138:139], v[194:195]
	v_pk_fma_f32 v[80:81], v[80:81], v[140:141], v[208:209]
	v_pk_fma_f32 v[82:83], v[82:83], v[142:143], v[210:211]
	v_cvt_pk_bf16_f32 v84, v84, v85
	v_cvt_pk_bf16_f32 v85, v86, v87
	v_cvt_pk_bf16_f32 v86, v80, v81
	v_cvt_pk_bf16_f32 v87, v82, v83
	s_waitcnt vmcnt(9)
; __device__ __forceinline__ unsigned cvt_pk_bf16(float lo, float hi) { unsigned r; asm("v_cvt_pk_bf16_f32 %0, %1, %2" : "=v"(r) : "v"(lo), "v"(hi)); return r; }
;     __device__ __forceinline__ void operator()(const Acc& acc, const Unit& u, int wr, int wc, int fr, int fq) const {
;     ...
;             for (int m = 0; m < 4; ++m) { const size_t off = (size_t)(r0 + ai * 128 + m * 16) * D + col0;
; #pragma unroll
;                 for (int bj = 0; bj < 2; ++bj) { const size_t o2 = off + bj * 128; f32x4 s0, s1;
;                     if (SRC32) { s0 = *(const f32x4*)(sp32 + o2); s1 = *(const f32x4*)(sp32 + o2 + 4); }
;                     else { const u32x4 q = *(const u32x4*)(sp16 + o2); s0 = (f32x4){bf2f(q.x & 0xffffu), bf2f(q.x >> 16), bf2f(q.y & 0xffffu), bf2f(q.y >> 16)}; s1 = (f32x4){bf2f(q.z & 0xffffu), bf2f(q.z >> 16), bf2f(q.w & 0xffffu), bf2f(q.w >> 16)}; }
;                     const f32x4 v0 = s0 + gv[bj][0] * acc[ai][bj][m][0], v1 = s1 + gv[bj][1] * acc[ai][bj][m][1];
;                     if (DST32) { *(f32x4*)(dp32 + o2) = v0; *(f32x4*)(dp32 + o2 + 4) = v1; }
;                     else { u32x4 w; w.x = cvt_pk_bf16(v0.x, v0.y); w.y = cvt_pk_bf16(v0.z, v0.w); w.z = cvt_pk_bf16(v1.x, v1.y); w.w = cvt_pk_bf16(v1.z, v1.w); *(u32x4*)(dp16 + o2) = w; } } }
	v_lshlrev_b32_e32 v192, 16, v212
	v_and_b32_e32 v193, 0xffff0000, v212
	v_lshlrev_b32_e32 v194, 16, v213
	v_and_b32_e32 v195, 0xffff0000, v213
	v_lshlrev_b32_e32 v212, 16, v214
	v_and_b32_e32 v213, 0xffff0000, v214
	v_lshlrev_b32_e32 v214, 16, v215
	v_and_b32_e32 v215, 0xffff0000, v215
	v_pk_fma_f32 v[76:77], v[76:77], v[128:129], v[192:193]
	v_pk_fma_f32 v[78:79], v[78:79], v[130:131], v[194:195]
	v_pk_fma_f32 v[72:73], v[72:73], v[132:133], v[212:213]
	v_pk_fma_f32 v[74:75], v[74:75], v[134:135], v[214:215]
	v_cvt_pk_bf16_f32 v76, v76, v77
	v_cvt_pk_bf16_f32 v77, v78, v79
	v_cvt_pk_bf16_f32 v78, v72, v73
	v_cvt_pk_bf16_f32 v79, v74, v75
	s_waitcnt vmcnt(8)
	v_lshlrev_b32_e32 v192, 16, v216
	v_and_b32_e32 v193, 0xffff0000, v216
	v_lshlrev_b32_e32 v194, 16, v217
	v_and_b32_e32 v195, 0xffff0000, v217
	v_lshlrev_b32_e32 v216, 16, v218
	v_and_b32_e32 v217, 0xffff0000, v218
	v_lshlrev_b32_e32 v218, 16, v219
	v_and_b32_e32 v219, 0xffff0000, v219
	v_pk_fma_f32 v[68:69], v[68:69], v[136:137], v[192:193]
	v_pk_fma_f32 v[70:71], v[70:71], v[138:139], v[194:195]
	v_pk_fma_f32 v[64:65], v[64:65], v[140:141], v[216:217]
	v_pk_fma_f32 v[66:67], v[66:67], v[142:143], v[218:219]
	v_cvt_pk_bf16_f32 v68, v68, v69
	v_cvt_pk_bf16_f32 v69, v70, v71
	v_cvt_pk_bf16_f32 v70, v64, v65
	v_cvt_pk_bf16_f32 v71, v66, v67
	s_waitcnt vmcnt(7)
	v_lshlrev_b32_e32 v192, 16, v220
	v_and_b32_e32 v193, 0xffff0000, v220
	v_lshlrev_b32_e32 v194, 16, v221
	v_and_b32_e32 v195, 0xffff0000, v221
	v_lshlrev_b32_e32 v220, 16, v222
	v_and_b32_e32 v221, 0xffff0000, v222
	v_lshlrev_b32_e32 v222, 16, v223
	v_and_b32_e32 v223, 0xffff0000, v223
	v_pk_fma_f32 v[60:61], v[60:61], v[128:129], v[192:193]
	v_pk_fma_f32 v[62:63], v[62:63], v[130:131], v[194:195]
	v_pk_fma_f32 v[56:57], v[56:57], v[132:133], v[220:221]
	v_pk_fma_f32 v[58:59], v[58:59], v[134:135], v[222:223]
	v_cvt_pk_bf16_f32 v60, v60, v61
	v_cvt_pk_bf16_f32 v61, v62, v63
	v_cvt_pk_bf16_f32 v62, v56, v57
	v_cvt_pk_bf16_f32 v63, v58, v59
	s_waitcnt vmcnt(6)
	v_lshlrev_b32_e32 v192, 16, v224
	v_and_b32_e32 v193, 0xffff0000, v224
	v_lshlrev_b32_e32 v194, 16, v225
	v_and_b32_e32 v195, 0xffff0000, v225
	v_lshlrev_b32_e32 v224, 16, v226
	v_and_b32_e32 v225, 0xffff0000, v226
	v_lshlrev_b32_e32 v226, 16, v227
	v_and_b32_e32 v227, 0xffff0000, v227
	v_pk_fma_f32 v[52:53], v[52:53], v[136:137], v[192:193]
	v_pk_fma_f32 v[54:55], v[54:55], v[138:139], v[194:195]
	v_pk_fma_f32 v[48:49], v[48:49], v[140:141], v[224:225]
	v_pk_fma_f32 v[50:51], v[50:51], v[142:143], v[226:227]
	v_cvt_pk_bf16_f32 v52, v52, v53
	v_cvt_pk_bf16_f32 v53, v54, v55
	v_cvt_pk_bf16_f32 v54, v48, v49
	v_cvt_pk_bf16_f32 v55, v50, v51
	s_waitcnt vmcnt(5)
	v_lshlrev_b32_e32 v192, 16, v228
	v_and_b32_e32 v193, 0xffff0000, v228
	v_lshlrev_b32_e32 v194, 16, v229
	v_and_b32_e32 v195, 0xffff0000, v229
	v_lshlrev_b32_e32 v228, 16, v230
	v_and_b32_e32 v229, 0xffff0000, v230
	v_lshlrev_b32_e32 v230, 16, v231
	v_and_b32_e32 v231, 0xffff0000, v231
	v_pk_fma_f32 v[44:45], v[44:45], v[128:129], v[192:193]
	v_pk_fma_f32 v[46:47], v[46:47], v[130:131], v[194:195]
	v_pk_fma_f32 v[40:41], v[40:41], v[132:133], v[228:229]
	v_pk_fma_f32 v[42:43], v[42:43], v[134:135], v[230:231]
	v_cvt_pk_bf16_f32 v44, v44, v45
	v_cvt_pk_bf16_f32 v45, v46, v47
	v_cvt_pk_bf16_f32 v46, v40, v41
	v_cvt_pk_bf16_f32 v47, v42, v43
	s_waitcnt vmcnt(4)
	v_lshlrev_b32_e32 v192, 16, v232
	v_and_b32_e32 v193, 0xffff0000, v232
	v_lshlrev_b32_e32 v194, 16, v233
	v_and_b32_e32 v195, 0xffff0000, v233
	v_lshlrev_b32_e32 v232, 16, v234
	v_and_b32_e32 v233, 0xffff0000, v234
	v_lshlrev_b32_e32 v234, 16, v235
	v_and_b32_e32 v235, 0xffff0000, v235
	v_pk_fma_f32 v[28:29], v[28:29], v[136:137], v[192:193]
	v_pk_fma_f32 v[30:31], v[30:31], v[138:139], v[194:195]
	v_pk_fma_f32 v[24:25], v[24:25], v[140:141], v[232:233]
	v_pk_fma_f32 v[26:27], v[26:27], v[142:143], v[234:235]
	v_cvt_pk_bf16_f32 v28, v28, v29
	v_cvt_pk_bf16_f32 v29, v30, v31
	v_cvt_pk_bf16_f32 v30, v24, v25
	v_cvt_pk_bf16_f32 v31, v26, v27
	s_waitcnt vmcnt(3)
; __device__ __forceinline__ unsigned cvt_pk_bf16(float lo, float hi) { unsigned r; asm("v_cvt_pk_bf16_f32 %0, %1, %2" : "=v"(r) : "v"(lo), "v"(hi)); return r; }
; #define PG8_BAR __builtin_amdgcn_s_barrier()
; template <class Epi, class Sched, bool SWAPD = false>
; __device__ __forceinline__ void gemm_phase(LAS unsigned char* lds, const Gemm g, const Sched& S, const Epi& E) {
;     ...
;         cur = nxt; cA = nA; cB = nB; ++ui;
;         if (wr == 1) PG8_BAR;
;     __device__ __forceinline__ void operator()(const Acc& acc, const Unit& u, int wr, int wc, int fr, int fq) const {
;     ...
;             for (int m = 0; m < 4; ++m) { const size_t off = (size_t)(r0 + ai * 128 + m * 16) * D + col0;
; #pragma unroll
;                 for (int bj = 0; bj < 2; ++bj) { const size_t o2 = off + bj * 128; f32x4 s0, s1;
;                     if (SRC32) { s0 = *(const f32x4*)(sp32 + o2); s1 = *(const f32x4*)(sp32 + o2 + 4); }
;                     else { const u32x4 q = *(const u32x4*)(sp16 + o2); s0 = (f32x4){bf2f(q.x & 0xffffu), bf2f(q.x >> 16), bf2f(q.y & 0xffffu), bf2f(q.y >> 16)}; s1 = (f32x4){bf2f(q.z & 0xffffu), bf2f(q.z >> 16), bf2f(q.w & 0xffffu), bf2f(q.w >> 16)}; }
;                     const f32x4 v0 = s0 + gv[bj][0] * acc[ai][bj][m][0], v1 = s1 + gv[bj][1] * acc[ai][bj][m][1];
;                     if (DST32) { *(f32x4*)(dp32 + o2) = v0; *(f32x4*)(dp32 + o2 + 4) = v1; }
;                     else { u32x4 w; w.x = cvt_pk_bf16(v0.x, v0.y); w.y = cvt_pk_bf16(v0.z, v0.w); w.z = cvt_pk_bf16(v1.x, v1.y); w.w = cvt_pk_bf16(v1.z, v1.w); *(u32x4*)(dp16 + o2) = w; } } }
	v_lshlrev_b32_e32 v192, 16, v144
	v_and_b32_e32 v193, 0xffff0000, v144
	v_lshlrev_b32_e32 v194, 16, v145
	v_and_b32_e32 v195, 0xffff0000, v145
	v_lshlrev_b32_e32 v144, 16, v146
	v_and_b32_e32 v145, 0xffff0000, v146
	v_lshlrev_b32_e32 v146, 16, v147
	v_and_b32_e32 v147, 0xffff0000, v147
	v_pk_fma_f32 v[36:37], v[36:37], v[128:129], v[192:193]
	v_pk_fma_f32 v[38:39], v[38:39], v[130:131], v[194:195]
	v_pk_fma_f32 v[32:33], v[32:33], v[132:133], v[144:145]
	v_pk_fma_f32 v[34:35], v[34:35], v[134:135], v[146:147]
	v_cvt_pk_bf16_f32 v36, v36, v37
	v_cvt_pk_bf16_f32 v37, v38, v39
	v_cvt_pk_bf16_f32 v38, v32, v33
	v_cvt_pk_bf16_f32 v39, v34, v35
	s_waitcnt vmcnt(2)
	v_lshlrev_b32_e32 v192, 16, v148
	v_and_b32_e32 v193, 0xffff0000, v148
	v_lshlrev_b32_e32 v194, 16, v149
	v_and_b32_e32 v195, 0xffff0000, v149
	v_lshlrev_b32_e32 v148, 16, v150
	v_and_b32_e32 v149, 0xffff0000, v150
	v_lshlrev_b32_e32 v150, 16, v151
	v_and_b32_e32 v151, 0xffff0000, v151
	v_pk_fma_f32 v[12:13], v[12:13], v[136:137], v[192:193]
	v_pk_fma_f32 v[14:15], v[14:15], v[138:139], v[194:195]
	v_pk_fma_f32 v[8:9], v[8:9], v[140:141], v[148:149]
	v_pk_fma_f32 v[10:11], v[10:11], v[142:143], v[150:151]
	v_cvt_pk_bf16_f32 v12, v12, v13
	v_cvt_pk_bf16_f32 v13, v14, v15
	v_cvt_pk_bf16_f32 v14, v8, v9
	v_cvt_pk_bf16_f32 v15, v10, v11
	s_waitcnt vmcnt(1)
	v_lshlrev_b32_e32 v192, 16, v152
	v_and_b32_e32 v193, 0xffff0000, v152
	v_lshlrev_b32_e32 v194, 16, v153
	v_and_b32_e32 v195, 0xffff0000, v153
	v_lshlrev_b32_e32 v152, 16, v154
	v_and_b32_e32 v153, 0xffff0000, v154
	v_lshlrev_b32_e32 v154, 16, v155
	v_and_b32_e32 v155, 0xffff0000, v155
	v_pk_fma_f32 v[20:21], v[20:21], v[128:129], v[192:193]
	v_pk_fma_f32 v[22:23], v[22:23], v[130:131], v[194:195]
	v_pk_fma_f32 v[16:17], v[16:17], v[132:133], v[152:153]
	v_pk_fma_f32 v[18:19], v[18:19], v[134:135], v[154:155]
	v_cvt_pk_bf16_f32 v20, v20, v21
	v_cvt_pk_bf16_f32 v21, v22, v23
	v_cvt_pk_bf16_f32 v22, v16, v17
	v_cvt_pk_bf16_f32 v23, v18, v19
	s_waitcnt vmcnt(0)
	v_lshlrev_b32_e32 v192, 16, v156
	v_and_b32_e32 v193, 0xffff0000, v156
	v_lshlrev_b32_e32 v194, 16, v157
	v_and_b32_e32 v195, 0xffff0000, v157
	v_lshlrev_b32_e32 v156, 16, v158
	v_and_b32_e32 v157, 0xffff0000, v158
	v_lshlrev_b32_e32 v158, 16, v159
	v_and_b32_e32 v159, 0xffff0000, v159
	v_pk_fma_f32 v[4:5], v[4:5], v[136:137], v[192:193]
	v_pk_fma_f32 v[6:7], v[6:7], v[138:139], v[194:195]
	v_pk_fma_f32 v[0:1], v[0:1], v[140:141], v[156:157]
	v_pk_fma_f32 v[2:3], v[2:3], v[142:143], v[158:159]
	v_cvt_pk_bf16_f32 v4, v4, v5
	v_cvt_pk_bf16_f32 v5, v6, v7
	v_cvt_pk_bf16_f32 v6, v0, v1
	v_cvt_pk_bf16_f32 v7, v2, v3
	v_lshl_add_u32 v196, v238, 1, v164
	global_store_dwordx4 v196, v[124:127], s[40:41]
	global_store_dwordx4 v196, v[108:111], s[40:41] offset:256
	v_lshl_add_u32 v197, v238, 1, v174
	global_store_dwordx4 v197, v[116:119], s[40:41]
	global_store_dwordx4 v197, v[100:103], s[40:41] offset:256
	v_lshl_add_u32 v196, v238, 1, v176
	global_store_dwordx4 v196, v[92:95], s[40:41]
	global_store_dwordx4 v196, v[84:87], s[40:41] offset:256
	v_lshl_add_u32 v197, v238, 1, v178
	global_store_dwordx4 v197, v[76:79], s[40:41]
	global_store_dwordx4 v197, v[68:71], s[40:41] offset:256
	v_lshl_add_u32 v196, v238, 1, v166
	global_store_dwordx4 v196, v[60:63], s[40:41]
	global_store_dwordx4 v196, v[52:55], s[40:41] offset:256
	v_lshl_add_u32 v197, v238, 1, v168
	global_store_dwordx4 v197, v[44:47], s[40:41]
	global_store_dwordx4 v197, v[28:31], s[40:41] offset:256
	v_lshl_add_u32 v196, v238, 1, v170
	global_store_dwordx4 v196, v[36:39], s[40:41]
	global_store_dwordx4 v196, v[12:15], s[40:41] offset:256
	v_lshl_add_u32 v197, v238, 1, v172
	global_store_dwordx4 v197, v[20:23], s[40:41]
	global_store_dwordx4 v197, v[4:7], s[40:41] offset:256
	s_andn2_b64 vcc, exec, s[4:5]
	s_mov_b64 s[4:5], -1
	s_cbranch_vccnz .LBB0_910
	s_andn2_b64 vcc, exec, s[8:9]
	s_cbranch_vccnz .LBB0_909
	s_barrier
	s_branch .LBB0_909
